# attention chains: sigmoid pair without sign selects (s=exp2(min(-z,126)), beta=1/(1+s), 1-beta=s*beta): 16 compares + 21 selects fewer, 16 mins more per chain; on top of one-copy rotation
# speedup vs baseline: 1.0037x; 1.0037x over previous
.LBB0_170:
	s_nop 7
	v_cmp_le_f32_e32 vcc, 0, v47
	v_exp_f32_e64 v47, -|v47|
	s_nop 0
	v_add_f32_e32 v48, 1.0, v47
	v_rcp_f32_e32 v48, v48
	s_nop 0
	v_mul_f32_e32 v49, v47, v48
	v_cndmask_b32_e32 v47, v49, v48, vcc
	v_cndmask_b32_e32 v48, v48, v49, vcc
	v_cmp_le_f32_e32 vcc, 0, v46
	v_exp_f32_e64 v46, -|v46|
	v_cndmask_b32_e64 v48, 1.0, v48, s[70:71]
	v_cndmask_b32_e64 v47, 0, v47, s[70:71]
	v_add_f32_e32 v49, 1.0, v46
	v_rcp_f32_e32 v49, v49
	s_nop 0
	v_mul_f32_e32 v50, v46, v49
	v_cndmask_b32_e32 v46, v50, v49, vcc
	v_cndmask_b32_e32 v49, v49, v50, vcc
	v_cmp_le_f32_e32 vcc, 0, v45
	v_exp_f32_e64 v45, -|v45|
	v_cndmask_b32_e64 v49, 1.0, v49, s[68:69]
	v_mul_f32_e32 v49, v49, v48
	v_cndmask_b32_e64 v46, 0, v46, s[68:69]
	v_add_f32_e32 v50, 1.0, v45
	v_rcp_f32_e32 v50, v50
	s_nop 0
	v_mul_f32_e32 v51, v45, v50
	v_cndmask_b32_e32 v45, v51, v50, vcc
	v_cndmask_b32_e32 v50, v50, v51, vcc
	v_cmp_le_f32_e32 vcc, 0, v44
	v_exp_f32_e64 v44, -|v44|
	v_cndmask_b32_e64 v50, 1.0, v50, s[66:67]
	v_mul_f32_e32 v50, v50, v49
	v_cndmask_b32_e64 v45, 0, v45, s[66:67]
	v_add_f32_e32 v51, 1.0, v44
	v_rcp_f32_e32 v51, v51
	s_nop 0
	v_mul_f32_e32 v52, v44, v51
	v_cndmask_b32_e32 v44, v52, v51, vcc
	v_cndmask_b32_e32 v51, v51, v52, vcc
	v_cmp_le_f32_e32 vcc, 0, v43
	v_exp_f32_e64 v43, -|v43|
	v_cndmask_b32_e64 v51, 1.0, v51, s[64:65]
	v_mul_f32_e32 v51, v51, v50
	v_cndmask_b32_e64 v44, 0, v44, s[64:65]
	v_add_f32_e32 v52, 1.0, v43
	v_rcp_f32_e32 v52, v52
	s_nop 0
	v_mul_f32_e32 v53, v43, v52
	v_cndmask_b32_e32 v43, v53, v52, vcc
	v_cndmask_b32_e32 v52, v52, v53, vcc
	v_cmp_le_f32_e32 vcc, 0, v42
	v_exp_f32_e64 v42, -|v42|
	v_cndmask_b32_e64 v52, 1.0, v52, s[62:63]
	v_mul_f32_e32 v52, v52, v51
	v_cndmask_b32_e64 v43, 0, v43, s[62:63]
	v_add_f32_e32 v53, 1.0, v42
	v_rcp_f32_e32 v53, v53
	s_nop 0
	v_mul_f32_e32 v54, v42, v53
	v_cndmask_b32_e32 v42, v54, v53, vcc
	v_cndmask_b32_e32 v53, v53, v54, vcc
	v_cmp_le_f32_e32 vcc, 0, v41
	v_exp_f32_e64 v41, -|v41|
	v_cndmask_b32_e64 v53, 1.0, v53, s[60:61]
	v_mul_f32_e32 v53, v53, v52
	v_cndmask_b32_e64 v42, 0, v42, s[60:61]
	v_add_f32_e32 v54, 1.0, v41
	v_rcp_f32_e32 v54, v54
	s_nop 0
	v_mul_f32_e32 v55, v41, v54
	v_cndmask_b32_e32 v41, v55, v54, vcc
	v_cndmask_b32_e32 v54, v54, v55, vcc
	v_cmp_le_f32_e32 vcc, 0, v40
	v_exp_f32_e64 v40, -|v40|
	v_cndmask_b32_e64 v54, 1.0, v54, s[58:59]
	v_mul_f32_e32 v54, v54, v53
	v_cndmask_b32_e64 v41, 0, v41, s[58:59]
	v_add_f32_e32 v55, 1.0, v40
	v_rcp_f32_e32 v55, v55
	s_nop 0
	v_mul_f32_e32 v40, v40, v55
	v_cndmask_b32_e32 v56, v40, v55, vcc
	v_cndmask_b32_e32 v40, v55, v40, vcc
	v_cmp_le_f32_e32 vcc, 0, v39
	v_exp_f32_e64 v39, -|v39|
	v_cndmask_b32_e64 v40, 1.0, v40, s[56:57]
	v_cndmask_b32_e64 v56, 0, v56, s[56:57]
	v_add_f32_e32 v55, 1.0, v39
	v_rcp_f32_e32 v55, v55
	s_nop 0
	v_mul_f32_e32 v39, v39, v55
	v_cndmask_b32_e32 v57, v39, v55, vcc
	v_cndmask_b32_e32 v39, v55, v39, vcc
	v_cmp_le_f32_e32 vcc, 0, v38
	v_exp_f32_e64 v38, -|v38|
	v_cndmask_b32_e64 v39, 1.0, v39, s[54:55]
	v_cndmask_b32_e64 v57, 0, v57, s[54:55]
	v_add_f32_e32 v55, 1.0, v38
	v_rcp_f32_e32 v55, v55
	s_nop 0
	v_mul_f32_e32 v38, v38, v55
	v_cndmask_b32_e32 v58, v38, v55, vcc
	v_cndmask_b32_e32 v38, v55, v38, vcc
	v_cmp_le_f32_e32 vcc, 0, v37
	v_exp_f32_e64 v37, -|v37|
	v_cndmask_b32_e64 v38, 1.0, v38, s[52:53]
	v_mul_f32_e32 v38, v38, v39
	v_cndmask_b32_e64 v58, 0, v58, s[52:53]
	v_add_f32_e32 v55, 1.0, v37
	v_rcp_f32_e32 v55, v55
	s_nop 0
	v_mul_f32_e32 v37, v37, v55
	v_cndmask_b32_e32 v59, v37, v55, vcc
	v_cndmask_b32_e32 v37, v55, v37, vcc
	v_cmp_le_f32_e32 vcc, 0, v36
	v_exp_f32_e64 v36, -|v36|
	v_cndmask_b32_e64 v37, 1.0, v37, s[50:51]
	v_mul_f32_e32 v37, v37, v38
	v_cndmask_b32_e64 v59, 0, v59, s[50:51]
	v_add_f32_e32 v55, 1.0, v36
	v_rcp_f32_e32 v55, v55
	s_nop 0
	v_mul_f32_e32 v36, v36, v55
	v_cndmask_b32_e32 v60, v36, v55, vcc
	v_cndmask_b32_e32 v36, v55, v36, vcc
	v_cmp_le_f32_e32 vcc, 0, v35
	v_exp_f32_e64 v35, -|v35|
	v_cndmask_b32_e64 v36, 1.0, v36, s[48:49]
	v_mul_f32_e32 v36, v36, v37
	v_cndmask_b32_e64 v60, 0, v60, s[48:49]
	v_add_f32_e32 v55, 1.0, v35
	v_rcp_f32_e32 v55, v55
	s_nop 0
	v_mul_f32_e32 v35, v35, v55
	v_cndmask_b32_e32 v61, v35, v55, vcc
	v_cndmask_b32_e32 v35, v55, v35, vcc
	v_cmp_le_f32_e32 vcc, 0, v34
	v_exp_f32_e64 v34, -|v34|
	v_cndmask_b32_e64 v35, 1.0, v35, s[46:47]
	v_mul_f32_e32 v35, v35, v36
	v_cndmask_b32_e64 v61, 0, v61, s[46:47]
	v_add_f32_e32 v55, 1.0, v34
	v_rcp_f32_e32 v55, v55
	s_nop 0
	v_mul_f32_e32 v34, v34, v55
	v_cndmask_b32_e32 v62, v34, v55, vcc
	v_cndmask_b32_e32 v34, v55, v34, vcc
	v_cmp_le_f32_e32 vcc, 0, v33
	v_exp_f32_e64 v33, -|v33|
	v_cndmask_b32_e64 v34, 1.0, v34, s[44:45]
	v_mul_f32_e32 v34, v34, v35
	v_cndmask_b32_e64 v62, 0, v62, s[44:45]
	v_add_f32_e32 v55, 1.0, v33
	v_rcp_f32_e32 v55, v55
	s_nop 0
	v_mul_f32_e32 v33, v33, v55
	v_cndmask_b32_e32 v63, v33, v55, vcc
	v_cndmask_b32_e32 v33, v55, v33, vcc
	v_cmp_le_f32_e32 vcc, 0, v32
	v_exp_f32_e64 v32, -|v32|
	v_cndmask_b32_e64 v33, 1.0, v33, s[42:43]
	v_mul_f32_e32 v33, v33, v34
	v_cndmask_b32_e64 v63, 0, v63, s[42:43]
	v_add_f32_e32 v55, 1.0, v32
	v_rcp_f32_e32 v55, v55
	s_nop 0
	v_mul_f32_e32 v32, v32, v55
	v_cndmask_b32_e32 v64, v32, v55, vcc
	v_cndmask_b32_e32 v32, v55, v32, vcc
	v_cndmask_b32_e64 v32, 1.0, v32, s[40:41]
	v_mul_f32_e32 v55, v32, v33
	v_mul_f32_e32 v32, v40, v54
	ds_bpermute_b32 v40, v245, v55
	ds_bpermute_b32 v65, v245, v32
	v_cndmask_b32_e64 v64, 0, v64, s[40:41]
	s_waitcnt lgkmcnt(0)
; #define LAS __attribute__((address_space(3)))
; __device__ __forceinline__ void mixer_unit(LAS unsigned char* lds, int unit, const bf16* P, bf16* Y, const float* conv_w, const float* sgu_norm, const float* sgu_w, const float* sgu_b, int tid, int wave, int lane) {
;     ...
;         for (int k0 = t0 + 32;; k0 -= 32) {
;             const bool doA = actA && (k0 <= t0);
;             f32x16 zB = {}, zA = {};
;             if (actB) {
; #pragma unroll
;                 for (int ks = 0; ks < 4; ++ks) zB = __builtin_amdgcn_mfma_f32_32x32x16_bf16(kfn[ks], Qs[(4 + ks) * 64 + lane], zB, 0, 0, 0); }
;             if (doA) {
; #pragma unroll
;                 for (int ks = 0; ks < 4; ++ks) zA = __builtin_amdgcn_mfma_f32_32x32x16_bf16(kfn[ks], Qs[ks * 64 + lane], zA, 0, 0, 0); }
; #pragma unroll
;             for (int i = 0; i < 4; ++i) { const int key = (lane >> 3) + 8 * i, c = lane & 7; *(LAS v4u*)(Vr + key * 96 + 8 * c) = vvn[i]; }
; #pragma unroll
;             for (int ks = 0; ks < 4; ++ks) kfn[ks] = kf2[ks];
; #pragma unroll
;             for (int i = 0; i < 4; ++i) vvn[i] = vv2[i];
;             if (k0 >= 64) { const bf16* kp = P + (size_t)(k0 - 64 + pr) * NIN + 1792 + hd * 64 + 8 * h;
; #pragma unroll
;                 for (int ks = 0; ks < 4; ++ks) kf2[ks] = *(const __attribute__((address_space(1))) bf16x8*)(kp + 16 * ks);
; #pragma unroll
;                 for (int i = 0; i < 4; ++i) vv2[i] = *(const __attribute__((address_space(1))) v4u*)(P + (size_t)(k0 - 64 + (lane >> 3) + 8 * i) * NIN + 2304 + hd * 64 + 8 * (lane & 7)); }
;             if (actB) { const bool dg = (k0 == t0 + 32); SB_CHAIN(zB, oacc[1][0], oacc[1][1], lsB, dg);
;                 if (__builtin_amdgcn_ballot_w64(lsB > 1e-37f) == 0ull) actB = false; }
;             if (doA) { const bool dg = (k0 == t0); SB_CHAIN(zA, oacc[0][0], oacc[0][1], lsA, dg);
;                 if (__builtin_amdgcn_ballot_w64(lsA > 1e-37f) == 0ull) actA = false; }
;             if (k0 < 32 || !(actA || actB)) break;
;         }
	v_mul_f32_e32 v68, v32, v65
	v_cndmask_b32_e64 v32, 1.0, v40, s[38:39]
	v_mul_f32_e32 v69, v32, v68
	v_mul_f32_e32 v32, v64, v33
	v_mul_f32_e32 v33, v63, v34
	v_mul_f32_e32 v32, v32, v69
	v_mul_f32_e32 v33, v33, v69
	v_cndmask_b32_e64 v67, 1.0, v65, s[38:39]
	v_cvt_pk_bf16_f32 v32, v32, v33
	v_mul_f32_e32 v33, v56, v54
	v_mul_f32_e32 v34, v41, v53
	v_mul_f32_e32 v33, v67, v33
	v_mul_f32_e32 v34, v67, v34
	v_cvt_pk_bf16_f32 v64, v33, v34
	v_mul_f32_e32 v33, v62, v35
	v_mul_f32_e32 v34, v61, v36
	v_mul_f32_e32 v33, v33, v69
	v_mul_f32_e32 v34, v34, v69
	v_cvt_pk_bf16_f32 v33, v33, v34
	v_mul_f32_e32 v34, v42, v52
	v_mul_f32_e32 v35, v43, v51
	v_mul_f32_e32 v34, v67, v34
	v_mul_f32_e32 v35, v67, v35
	v_cvt_pk_bf16_f32 v65, v34, v35
	v_mul_f32_e32 v34, v60, v37
	v_mul_f32_e32 v35, v59, v38
	v_mul_f32_e32 v34, v34, v69
	v_mul_f32_e32 v35, v35, v69
	v_cvt_pk_bf16_f32 v34, v34, v35
	v_mul_f32_e32 v35, v44, v50
	v_mul_f32_e32 v35, v35, v67
	v_mul_f32_e32 v36, v45, v49
	v_mul_f32_e32 v36, v36, v67
	v_cvt_pk_bf16_f32 v66, v35, v36
	v_mul_f32_e32 v35, v58, v39
	v_mul_f32_e32 v35, v35, v69
	v_mul_f32_e32 v36, v57, v69
	v_cvt_pk_bf16_f32 v35, v35, v36
	v_mul_f32_e32 v36, v46, v48
	v_mul_f32_e32 v36, v36, v67
	v_mul_f32_e32 v37, v47, v67
	v_cvt_pk_bf16_f32 v67, v36, v37
	v_mul_f32_e32 v36, v55, v40
	v_mul_f32_e32 v214, v36, v68
	ds_read_b64_tr_b16 v[36:37], v244
	ds_read_b64_tr_b16 v[38:39], v244 offset:768
	s_waitcnt lgkmcnt(0)
	v_mfma_f32_32x32x16_bf16 v[48:63], v[36:39], v[32:35], 0
	ds_read_b64_tr_b16 v[36:37], v244 offset:3072
	ds_read_b64_tr_b16 v[38:39], v244 offset:3840
	v_cmp_lt_f32_e32 vcc, s26, v214
	s_cmp_lg_u64 vcc, 0
	s_cselect_b64 s[8:9], -1, 0
	s_cmp_lg_u32 s2, 0
	s_cselect_b64 s[0:1], -1, 0
	s_or_b64 s[10:11], s[6:7], s[8:9]
	s_waitcnt lgkmcnt(0)
	v_mfma_f32_32x32x16_bf16 v[48:63], v[36:39], v[64:67], v[48:63]
	ds_read_b64_tr_b16 v[36:37], v244 offset:64
	ds_read_b64_tr_b16 v[38:39], v244 offset:832
	ds_read_b64_tr_b16 v[68:69], v244 offset:3136
	ds_read_b64_tr_b16 v[70:71], v244 offset:3904
	s_and_b64 s[0:1], s[0:1], s[10:11]
	s_andn2_b64 vcc, exec, s[0:1]
	s_waitcnt lgkmcnt(2)
	v_mfma_f32_32x32x16_bf16 v[32:47], v[36:39], v[32:35], 0
	s_waitcnt lgkmcnt(0)
	v_mfma_f32_32x32x16_bf16 v[32:47], v[68:71], v[64:67], v[32:47]
	s_cbranch_vccnz .LBB0_184
	v_lshl_add_u64 v[216:217], v[206:207], 1, s[20:21]
	s_mov_b32 s5, s28
	s_mov_b32 s100, 0x42fc0000
	s_waitcnt vmcnt(0)

.LBB0_179:
	v_min_f32_e64 v81, -v79, s100
	v_exp_f32_e32 v81, v81
	v_min_f32_e64 v80, -v71, s100
	v_exp_f32_e32 v80, v80
	v_min_f32_e64 v83, -v78, s100
	v_exp_f32_e32 v83, v83
	v_min_f32_e64 v85, -v77, s100
	v_exp_f32_e32 v85, v85
	v_min_f32_e64 v82, -v70, s100
	v_exp_f32_e32 v82, v82
	v_min_f32_e64 v87, -v76, s100
	v_exp_f32_e32 v87, v87
	v_min_f32_e64 v84, -v69, s100
	v_exp_f32_e32 v84, v84
	v_add_f32_e32 v160, 1.0, v81
	v_min_f32_e64 v89, -v75, s100
	v_exp_f32_e32 v89, v89
	v_min_f32_e64 v86, -v68, s100
	v_exp_f32_e32 v86, v86
	v_rcp_f32_e32 v161, v160
	v_add_f32_e32 v160, 1.0, v80
	v_min_f32_e64 v88, -v67, s100
	v_exp_f32_e32 v88, v88
	v_rcp_f32_e32 v160, v160
	v_add_f32_e32 v162, 1.0, v83
	v_min_f32_e64 v91, -v74, s100
	v_exp_f32_e32 v91, v91
	v_min_f32_e64 v93, -v73, s100
	v_exp_f32_e32 v93, v93
	v_rcp_f32_e32 v163, v162
	v_add_f32_e32 v162, 1.0, v82
	v_add_f32_e32 v78, 1.0, v85
	v_min_f32_e64 v90, -v66, s100
	v_exp_f32_e32 v90, v90
	v_min_f32_e64 v92, -v65, s100
	v_exp_f32_e32 v92, v92
	v_rcp_f32_e32 v162, v162
	v_rcp_f32_e32 v79, v78
	v_add_f32_e32 v78, 1.0, v84
	v_add_f32_e32 v164, 1.0, v87
	v_min_f32_e64 v95, -v72, s100
	v_exp_f32_e32 v95, v95
	v_rcp_f32_e32 v78, v78
	v_rcp_f32_e32 v165, v164
	v_add_f32_e32 v164, 1.0, v86
	v_add_f32_e32 v76, 1.0, v89
	v_min_f32_e64 v94, -v64, s100
	v_exp_f32_e32 v94, v94
	v_pk_mul_f32 v[80:81], v[80:81], v[160:161]
	v_rcp_f32_e32 v164, v164
	v_rcp_f32_e32 v77, v76
	v_add_f32_e32 v76, 1.0, v88
	v_rcp_f32_e32 v76, v76
	v_add_f32_e32 v166, 1.0, v91
	v_add_f32_e32 v75, 1.0, v93
	v_mov_b32_e32 v73, v81
	v_pk_mul_f32 v[82:83], v[82:83], v[162:163]
	v_rcp_f32_e32 v167, v166
	v_add_f32_e32 v166, 1.0, v90
	v_rcp_f32_e32 v169, v75
	v_add_f32_e32 v75, 1.0, v92
	v_mov_b32_e32 v72, v80
	v_pk_mul_f32 v[84:85], v[84:85], v[78:79]
	v_rcp_f32_e32 v166, v166
	v_rcp_f32_e32 v168, v75
	v_add_f32_e32 v75, 1.0, v95
	v_mov_b32_e32 v70, v82
	v_pk_mul_f32 v[86:87], v[86:87], v[164:165]
	v_rcp_f32_e32 v171, v75
	v_add_f32_e32 v75, 1.0, v94
	v_mov_b32_e32 v71, v83
	v_mov_b32_e32 v81, v78
	v_pk_mul_f32 v[88:89], v[88:89], v[76:77]
	v_rcp_f32_e32 v170, v75
	v_mov_b32_e32 v68, v86
	v_pk_mul_f32 v[70:71], v[70:71], v[72:73]
	v_mov_b32_e32 v174, v79
	v_mov_b32_e32 v176, v77
	v_mov_b32_e32 v69, v87
	v_mov_b32_e32 v87, v76
	v_mul_f32_e32 v76, v84, v70
	v_mul_f32_e32 v77, v85, v71
	v_pk_mul_f32 v[90:91], v[90:91], v[166:167]
	v_pk_mul_f32 v[68:69], v[68:69], v[76:77]
	v_pk_mul_f32 v[92:93], v[92:93], v[168:169]
	v_mul_f32_e32 v78, v88, v68
	v_mul_f32_e32 v79, v89, v69
	v_pk_mul_f32 v[94:95], v[94:95], v[170:171]
	v_mul_f32_e32 v66, v90, v78
	v_mul_f32_e32 v67, v91, v79
	v_mul_f32_e32 v74, v92, v66
	v_mul_f32_e32 v75, v93, v67
	v_mul_f32_e32 v64, v94, v74
	v_mul_f32_e32 v65, v95, v75
	ds_bpermute_b32 v82, v245, v64
	ds_bpermute_b32 v83, v245, v65
	s_waitcnt lgkmcnt(1)
	v_cndmask_b32_e64 v92, 1.0, v82, s[38:39]
	s_waitcnt lgkmcnt(0)
	v_pk_mul_f32 v[84:85], v[64:65], v[82:83]
	v_mul_f32_e32 v82, v170, v74
	v_mul_f32_e32 v89, v168, v66
	v_mul_f32_e32 v90, v169, v67
	v_cndmask_b32_e64 v66, 1.0, v83, s[38:39]
	v_mov_b32_e32 v215, v79
	v_mul_f32_e32 v64, v171, v75
	v_mul_f32_e32 v74, v214, v66
	v_mul_f32_e32 v75, v215, v167
	v_mul_f32_e32 v65, v92, v85
	v_mul_f32_e32 v66, v74, v64
	v_mul_f32_e32 v64, v176, v69
	v_mul_f32_e32 v69, v74, v64
	v_mul_f32_e32 v64, v165, v77
	v_mul_f32_e32 v83, v64, v74
	v_mul_f32_e32 v64, v174, v71
	v_mul_f32_e32 v70, v81, v70
	v_mul_f32_e32 v71, v64, v74
	v_mov_b32_e32 v81, v214
	v_mov_b32_e32 v64, v72
	v_mul_f32_e32 v79, v164, v76
	v_mul_f32_e32 v76, v162, v64
	v_mul_f32_e32 v77, v81, v65
	v_mul_f32_e32 v78, v166, v78
	v_mul_f32_e32 v68, v87, v68
	v_mul_f32_e32 v67, v74, v90
	v_mul_f32_e32 v64, v82, v77
	v_mul_f32_e32 v65, v89, v77
	v_cvt_pk_bf16_f32 v64, v64, v65
	v_mul_f32_e32 v65, v78, v77
	v_mul_f32_e32 v72, v68, v77
	v_cvt_pk_bf16_f32 v68, v66, v67
	v_mul_f32_e32 v66, v79, v77
	v_mul_f32_e32 v67, v70, v77
	v_mul_f32_e32 v75, v74, v75
	v_cvt_pk_bf16_f32 v65, v65, v72
	v_cvt_pk_bf16_f32 v69, v75, v69
	v_cvt_pk_bf16_f32 v66, v66, v67
	v_cvt_pk_bf16_f32 v70, v83, v71
	v_mul_f32_e32 v67, v76, v77
	v_mul_f32_e32 v71, v160, v77
	v_cvt_pk_bf16_f32 v67, v67, v71
	v_mul_f32_e32 v71, v163, v73
	v_mul_f32_e32 v71, v71, v74
	v_mul_f32_e32 v72, v161, v74
	v_cvt_pk_bf16_f32 v71, v71, v72
	ds_read_b64_tr_b16 v[72:73], v244
	ds_read_b64_tr_b16 v[74:75], v244 offset:768
	ds_read_b64_tr_b16 v[78:79], v244 offset:832
	ds_read_b64_tr_b16 v[76:77], v244 offset:64
	s_waitcnt lgkmcnt(2)
	v_mfma_f32_32x32x16_bf16 v[48:63], v[72:75], v[64:67], v[48:63]
	ds_read_b64_tr_b16 v[72:73], v244 offset:3072
	ds_read_b64_tr_b16 v[74:75], v244 offset:3840
	ds_read_b64_tr_b16 v[82:83], v244 offset:3904
	ds_read_b64_tr_b16 v[80:81], v244 offset:3136
	s_waitcnt lgkmcnt(4)
	v_mfma_f32_32x32x16_bf16 v[32:47], v[76:79], v[64:67], v[32:47]
	v_mul_f32_e32 v64, v84, v85
	v_mul_f32_e32 v214, v214, v64
	v_cmp_lt_f32_e32 vcc, s26, v214
	s_cmp_lg_u64 vcc, 0
	s_cselect_b64 s[8:9], -1, 0
	s_waitcnt lgkmcnt(2)
	v_mfma_f32_32x32x16_bf16 v[48:63], v[72:75], v[68:71], v[48:63]
	s_waitcnt lgkmcnt(0)
	v_mfma_f32_32x32x16_bf16 v[32:47], v[80:83], v[68:71], v[32:47]

.LBB0_183:
	v_min_f32_e64 v161, -v95, s100
	v_exp_f32_e32 v161, v161
	v_min_f32_e64 v163, -v94, s100
	v_exp_f32_e32 v163, v163
	v_min_f32_e64 v162, -v87, s100
	v_exp_f32_e32 v162, v162
	v_min_f32_e64 v160, -v86, s100
	v_exp_f32_e32 v160, v160
	v_min_f32_e64 v165, -v93, s100
	v_exp_f32_e32 v165, v165
	v_min_f32_e64 v167, -v92, s100
	v_exp_f32_e32 v167, v167
	v_min_f32_e64 v164, -v85, s100
	v_exp_f32_e32 v164, v164
	v_min_f32_e64 v169, -v91, s100
	v_exp_f32_e32 v169, v169
	v_min_f32_e64 v166, -v84, s100
	v_exp_f32_e32 v166, v166
	v_add_f32_e32 v176, 1.0, v161
	v_add_f32_e32 v178, 1.0, v163
	v_min_f32_e64 v171, -v90, s100
	v_exp_f32_e32 v171, v171
	v_min_f32_e64 v168, -v83, s100
	v_exp_f32_e32 v168, v168
	v_rcp_f32_e32 v177, v176
	v_add_f32_e32 v176, 1.0, v160
	v_rcp_f32_e32 v179, v178
	v_add_f32_e32 v178, 1.0, v162
	v_min_f32_e64 v173, -v89, s100
	v_exp_f32_e32 v173, v173
	v_min_f32_e64 v170, -v82, s100
	v_exp_f32_e32 v170, v170
	v_rcp_f32_e32 v176, v176
	v_rcp_f32_e32 v178, v178
	v_add_f32_e32 v94, 1.0, v165
	v_min_f32_e64 v175, -v88, s100
	v_exp_f32_e32 v175, v175
	v_min_f32_e64 v172, -v81, s100
	v_exp_f32_e32 v172, v172
	v_rcp_f32_e32 v95, v94
	v_add_f32_e32 v94, 1.0, v164
	v_add_f32_e32 v180, 1.0, v167
	v_min_f32_e64 v174, -v80, s100
	v_exp_f32_e32 v174, v174
	v_rcp_f32_e32 v94, v94
	v_rcp_f32_e32 v181, v180
	v_add_f32_e32 v180, 1.0, v166
	v_add_f32_e32 v92, 1.0, v169
	v_rcp_f32_e32 v180, v180
	v_rcp_f32_e32 v93, v92
	v_add_f32_e32 v92, 1.0, v168
	v_add_f32_e32 v182, 1.0, v171
	v_pk_mul_f32 v[160:161], v[160:161], v[176:177]
	v_pk_mul_f32 v[162:163], v[162:163], v[178:179]
	v_rcp_f32_e32 v92, v92
	v_rcp_f32_e32 v183, v182
	v_add_f32_e32 v182, 1.0, v170
	v_add_f32_e32 v90, 1.0, v173
	v_rcp_f32_e32 v182, v182
	v_rcp_f32_e32 v91, v90
	v_add_f32_e32 v90, 1.0, v172
	v_add_f32_e32 v184, 1.0, v175
	v_mov_b32_e32 v87, v161
	v_pk_mul_f32 v[164:165], v[164:165], v[94:95]
	v_rcp_f32_e32 v90, v90
	v_rcp_f32_e32 v185, v184
	v_add_f32_e32 v184, 1.0, v174
	v_mov_b32_e32 v88, v162
	v_mov_b32_e32 v86, v160
	v_mov_b32_e32 v212, v176
	v_pk_mul_f32 v[166:167], v[166:167], v[180:181]
	v_rcp_f32_e32 v184, v184
	v_mov_b32_e32 v176, v94
	v_mul_f32_e32 v162, v86, v88
	v_mul_f32_e32 v163, v87, v163
	v_pk_mul_f32 v[168:169], v[168:169], v[92:93]
	v_mov_b32_e32 v85, v167
	v_mov_b32_e32 v84, v166
	v_mul_f32_e32 v160, v164, v162
	v_mul_f32_e32 v161, v165, v163
	v_mov_b32_e32 v188, v95
	v_pk_mul_f32 v[170:171], v[170:171], v[182:183]
	v_mov_b32_e32 v167, v92
	v_pk_mul_f32 v[84:85], v[84:85], v[160:161]
	v_pk_mul_f32 v[172:173], v[172:173], v[90:91]
	v_mul_f32_e32 v94, v168, v84
	v_mul_f32_e32 v95, v169, v85
	v_mov_b32_e32 v190, v93
	v_pk_mul_f32 v[174:175], v[174:175], v[184:185]
	v_mul_f32_e32 v82, v170, v94
	v_mul_f32_e32 v83, v171, v95
	v_mul_f32_e32 v92, v172, v82
	v_mul_f32_e32 v93, v173, v83
	v_mul_f32_e32 v80, v174, v92
	v_mul_f32_e32 v81, v175, v93
	ds_bpermute_b32 v165, v245, v81
	ds_bpermute_b32 v164, v245, v80
	v_mov_b32_e32 v215, v91
	s_waitcnt lgkmcnt(1)
	v_cndmask_b32_e64 v89, 1.0, v165, s[38:39]
	v_mul_f32_e32 v168, v213, v89
	s_waitcnt lgkmcnt(0)
	v_cndmask_b32_e64 v89, 1.0, v164, s[38:39]
	v_pk_mul_f32 v[164:165], v[80:81], v[164:165]
	v_mul_f32_e32 v81, v90, v82
	v_mul_f32_e32 v90, v167, v84
	v_mul_f32_e32 v84, v183, v95
	v_mul_f32_e32 v89, v89, v165
	v_mul_f32_e32 v80, v184, v92
	v_mul_f32_e32 v91, v84, v168
	v_mul_f32_e32 v84, v190, v85
	v_mul_f32_e32 v82, v185, v93
	v_mul_f32_e32 v85, v84, v168
	v_mul_f32_e32 v84, v181, v161
	v_pk_mul_f32 v[88:89], v[212:213], v[88:89]
	v_mul_f32_e32 v82, v82, v168
	v_mul_f32_e32 v83, v215, v83
	v_mul_f32_e32 v86, v182, v94
	v_mul_f32_e32 v94, v84, v168
	v_mul_f32_e32 v84, v188, v163
	v_mul_f32_e32 v80, v80, v89
	v_mul_f32_e32 v81, v81, v89
	v_mul_f32_e32 v83, v83, v168
	v_mul_f32_e32 v92, v180, v160
	v_mul_f32_e32 v93, v176, v162
	v_mul_f32_e32 v95, v84, v168
	v_cvt_pk_bf16_f32 v80, v80, v81
	v_cvt_pk_bf16_f32 v84, v82, v83
	v_mul_f32_e32 v81, v86, v89
	v_mul_f32_e32 v82, v90, v89
	v_cvt_pk_bf16_f32 v81, v81, v82
	v_mul_f32_e32 v82, v92, v89
	v_mul_f32_e32 v83, v93, v89
	v_cvt_pk_bf16_f32 v85, v91, v85
	v_cvt_pk_bf16_f32 v82, v82, v83
	v_mul_f32_e32 v83, v88, v89
	v_mul_f32_e32 v88, v178, v89
	v_mul_f32_e32 v87, v179, v87
	v_cvt_pk_bf16_f32 v86, v94, v95
	v_cvt_pk_bf16_f32 v83, v83, v88
	v_mul_f32_e32 v87, v87, v168
	v_mul_f32_e32 v88, v177, v168
	v_cvt_pk_bf16_f32 v87, v87, v88
	ds_read_b64_tr_b16 v[88:89], v244
	ds_read_b64_tr_b16 v[90:91], v244 offset:768
	ds_read_b64_tr_b16 v[94:95], v244 offset:832
	ds_read_b64_tr_b16 v[92:93], v244 offset:64
	s_waitcnt lgkmcnt(2)
	v_mfma_f32_32x32x16_bf16 v[0:15], v[88:91], v[80:83], v[0:15]
	ds_read_b64_tr_b16 v[88:89], v244 offset:3072
	ds_read_b64_tr_b16 v[90:91], v244 offset:3840
	ds_read_b64_tr_b16 v[162:163], v244 offset:3904
	ds_read_b64_tr_b16 v[160:161], v244 offset:3136
	s_waitcnt lgkmcnt(4)
	v_mfma_f32_32x32x16_bf16 v[16:31], v[92:95], v[80:83], v[16:31]
	v_mul_f32_e32 v80, v164, v165
	v_mul_f32_e32 v213, v213, v80
	v_cmp_lt_f32_e32 vcc, s26, v213
	s_cmp_lg_u64 vcc, 0
	s_cselect_b64 s[6:7], -1, 0
	s_waitcnt lgkmcnt(2)
	v_mfma_f32_32x32x16_bf16 v[0:15], v[88:91], v[84:87], v[0:15]
	s_waitcnt lgkmcnt(0)
	v_mfma_f32_32x32x16_bf16 v[16:31], v[160:163], v[84:87], v[16:31]
	s_and_b64 vcc, exec, s[40:41]
	s_cbranch_vccz .LBB0_179
	s_branch .LBB0_180
